# attention tile loops: packed max-subtract and row-sum tree, fp8 pack without zero init, V fragment addresses hoisted (P2a), incremental K/V DMA offsets for interior units (P2a)
# speedup vs baseline: 1.0029x; 1.0029x over previous
; #define GAS __attribute__((address_space(1)))
; __device__ __forceinline__ void at_dma_k(LAS unsigned char* kdst, const bf16_t* kbase, int tq0, int dil, int tile, int lane_) {
;     int lane = lane_; asm volatile("" : "+v"(lane));
;     const int r0 = lane >> 3; const unsigned c0 = (unsigned)(((lane & 7) ^ r0) << 4);
;     const int t0 = tq0 + dil * (32 * tile + r0 - 64), d8 = 8 * dil;
; #pragma unroll
;     for (int n = 0; n < 4; ++n) { int tkn = t0 + n * d8; tkn = tkn < 0 ? 0 : (tkn > SEQ - 1 ? SEQ - 1 : tkn);
;         const unsigned off = ((unsigned)tkn << 7) + c0;
;         __builtin_amdgcn_global_load_lds((const unsigned*)((const GAS char*)kbase + off), (LAS unsigned*)(kdst + n * 1024), 16, 0, 0); }
; }
; __device__ __forceinline__ long bf16x8_to_fp8(const bf16x8 v) {
;     const v4u w = __builtin_bit_cast(v4u, v);
;     int lo = __builtin_amdgcn_cvt_pk_fp8_f32(__builtin_bit_cast(float, w.x << 16), __builtin_bit_cast(float, w.x & 0xffff0000u), 0, false);
;     lo = __builtin_amdgcn_cvt_pk_fp8_f32(__builtin_bit_cast(float, w.y << 16), __builtin_bit_cast(float, w.y & 0xffff0000u), lo, true);
;     int hi = __builtin_amdgcn_cvt_pk_fp8_f32(__builtin_bit_cast(float, w.z << 16), __builtin_bit_cast(float, w.z & 0xffff0000u), 0, false);
;     hi = __builtin_amdgcn_cvt_pk_fp8_f32(__builtin_bit_cast(float, w.w << 16), __builtin_bit_cast(float, w.w & 0xffff0000u), hi, true);
;     return (long)(((unsigned long long)(unsigned)hi << 32) | (unsigned long long)(unsigned)lo);
; }
; __device__ __forceinline__ void at_dma_v(LAS unsigned char* vdst, const bf16_t* vbase, int tq0, int dil, int tile, int lane_) { at_dma_k(vdst, vbase, tq0, dil, tile, lane_); }
; template <int OFF> __device__ __forceinline__ long tr8_read(unsigned vb) {
;     long r; asm volatile("ds_read_b64_tr_b8 %0, %1 offset:%2" : "=&v"(r) : "v"(vb), "i"(OFF) : "memory"); return r;
; }
; __global__ void __launch_bounds__(NWAVES * 64, 2) mk_fwd(Args args) {
;     ...
;         int U = vwave;
;         if (U < NU) {
;             const bf16_t *cq, *ck, *cv, *nq, *nk, *nv; bf16_t *cp, *np_; float *cm, *nm; int ctq, cdl, ntq = 0, ndl = 1; float csl, nsl = 0.f;
;             AT_DEC_AB(U, cq, ck, cv, ctq, cdl, csl, cp, cm);
;             nq = cq; nk = ck; nv = cv; np_ = cp; nm = cm;
;             bf16x8 qr[8];
;             at_unit_prologue(wl, qr, cq, ck, cv, ctq, cdl, lna);
.LBB0_364:
	s_ashr_i32 s8, s86, 8
	s_ashr_i32 s9, s8, 31
	s_and_b32 s18, s8, 7
	s_lshl_b64 s[14:15], s[8:9], 19
	s_lshl_b64 s[16:17], s[8:9], 20
	s_add_u32 s12, s84, s16
	s_addc_u32 s13, s85, s17
	s_add_u32 s38, s94, 0x10400000
	s_addc_u32 s49, s95, 0
	s_add_u32 s54, s38, s14
	s_addc_u32 s55, s49, s15
	s_add_u32 s51, s94, 0x12400000
	s_addc_u32 s52, s95, 0
	s_add_u32 s56, s51, s14
	s_addc_u32 s57, s52, s15
	s_add_i32 s18, s18, 1
	v_cvt_f32_ubyte0_e32 v0, s18
	s_mov_b32 s53, 0x42fc0000
	v_mov_b32_e32 v133, 0x42800000
	v_cmp_lt_f32_e32 vcc, s53, v0
	s_and_b64 s[14:15], vcc, exec
	s_cselect_b32 s14, 0xffffffc0, 0
	v_cndmask_b32_e32 v1, 0, v133, vcc
	v_sub_f32_e32 v0, v1, v0
	v_exp_f32_e32 v0, v0
	v_readlane_b32 s20, v254, 2
	v_readlane_b32 s22, v254, 4
	v_readlane_b32 s23, v254, 5
	v_ldexp_f32 v0, v0, s14
	v_mul_f32_e32 v0, 0x3fb8aa3b, v0
	s_add_u32 s14, s22, s6
	v_cvt_f32_ubyte0_e32 v1, s88
	s_addc_u32 s15, s23, s7
	s_and_b32 s6, s86, s11
	v_mul_f32_e32 v128, v0, v1
	v_mov_b32_e32 v0, v131
	s_or_b32 s92, s10, s6
	s_lshl_b64 s[6:7], s[8:9], 15
	s_add_u32 s44, s14, s6
	v_ashrrev_i32_e32 v1, 3, v0
	v_bitop3_b32 v0, v0, v1, 7 bitop3:0x6c
	v_subrev_u32_e32 v1, 64, v1
	s_addc_u32 s45, s15, s7
	v_mul_lo_u32 v1, v1, s88
	s_add_u32 s16, s4, s16
	v_add_u32_e32 v1, s92, v1
	v_mov_b32_e32 v172, 0xfff
	s_addc_u32 s17, s5, s17
	v_lshlrev_b32_e32 v0, 4, v0
	v_med3_i32 v2, v1, 0, v172
	s_lshl_b32 s4, s88, 3
	s_mov_b32 m0, s83
	v_lshl_add_u32 v2, v2, 7, v0
	v_add_u32_e32 v1, s4, v1
	global_load_lds_dwordx4 v2, s[54:55]
	v_med3_i32 v2, v1, 0, v172
	s_add_i32 s76, s83, 0x400
	v_lshl_add_u32 v2, v2, 7, v0
	s_mov_b32 m0, s76
	v_add_u32_e32 v1, s4, v1
	global_load_lds_dwordx4 v2, s[54:55]
	v_med3_i32 v2, v1, 0, v172
	s_add_i32 s77, s83, 0x800
	v_add_u32_e32 v1, s4, v1
	v_lshl_add_u32 v2, v2, 7, v0
	s_mov_b32 m0, s77
	v_med3_i32 v1, v1, 0, v172
	s_add_i32 s78, s83, 0xc00
	global_load_lds_dwordx4 v2, s[54:55]
	v_lshl_add_u32 v0, v1, 7, v0
	s_mov_b32 m0, s78
	s_add_i32 s79, s83, 0x2000
	global_load_lds_dwordx4 v0, s[54:55]
	v_mov_b32_e32 v0, v131
	s_mov_b32 m0, s79
	v_ashrrev_i32_e32 v1, 3, v0
	v_bitop3_b32 v0, v0, v1, 7 bitop3:0x6c
	v_subrev_u32_e32 v1, 64, v1
	v_mul_lo_u32 v1, v1, s88
	v_add_u32_e32 v1, s92, v1
	v_lshlrev_b32_e32 v0, 4, v0
	v_med3_i32 v2, v1, 0, v172
	v_lshl_add_u32 v2, v2, 7, v0
	v_add_u32_e32 v1, s4, v1
	global_load_lds_dwordx4 v2, s[56:57]
	v_med3_i32 v2, v1, 0, v172
	s_add_i32 s80, s83, 0x2400
	v_lshl_add_u32 v2, v2, 7, v0
	s_mov_b32 m0, s80
	v_add_u32_e32 v1, s4, v1
	global_load_lds_dwordx4 v2, s[56:57]
	v_med3_i32 v2, v1, 0, v172
	s_add_i32 s81, s83, 0x2800
	v_add_u32_e32 v1, s4, v1
	v_lshl_add_u32 v2, v2, 7, v0
	s_mov_b32 m0, s81
	v_med3_i32 v1, v1, 0, v172
	s_add_i32 s82, s83, 0x2c00
	global_load_lds_dwordx4 v2, s[56:57]
	v_lshl_add_u32 v0, v1, 7, v0
	s_mov_b32 m0, s82
	v_and_b32_e32 v173, 31, v131
	global_load_lds_dwordx4 v0, s[56:57]
	v_mul_u32_u24_e32 v0, s88, v173
	v_ashrrev_i32_e32 v2, 2, v131
	v_add_lshl_u32 v112, v0, s92, 8
	v_mov_b32_e32 v113, 0
	v_and_b32_e32 v114, -8, v2
	v_lshl_add_u64 v[0:1], s[12:13], 0, v[112:113]
	v_ashrrev_i32_e32 v115, 31, v114
	v_lshl_add_u64 v[0:1], v[114:115], 1, v[0:1]
	global_load_dwordx4 v[80:83], v[0:1], off
	global_load_dwordx4 v[84:87], v[0:1], off offset:32
	global_load_dwordx4 v[88:91], v[0:1], off offset:64
	global_load_dwordx4 v[92:95], v[0:1], off offset:96
	global_load_dwordx4 v[96:99], v[0:1], off offset:128
	global_load_dwordx4 v[100:103], v[0:1], off offset:160
	global_load_dwordx4 v[104:107], v[0:1], off offset:192
	global_load_dwordx4 v[108:111], v[0:1], off offset:224
	v_ashrrev_i32_e32 v0, 5, v131
	v_lshlrev_b32_e32 v2, 3, v0
	v_lshlrev_b32_e32 v0, 2, v0
	v_sub_u32_e32 v0, v0, v173
	v_subrev_u32_e32 v175, 64, v0
	v_lshlrev_b32_e32 v0, 8, v173
	v_lshlrev_b32_e32 v3, 4, v131
	s_movk_i32 s6, 0x70
	v_add3_u32 v176, s83, v0, v2
	v_mov_b32_e32 v0, 0xf0
	v_bitop3_b32 v16, v3, s6, v3 bitop3:0xc
	v_bitop3_b32 v23, v3, s6, v0 bitop3:0x6c
	s_movk_i32 s6, 0x80
	v_bitop3_b32 v24, v3, s6, v0 bitop3:0x6c
	s_movk_i32 s6, 0x90
	v_bitop3_b32 v25, v3, s6, v0 bitop3:0x6c
	s_movk_i32 s6, 0xa0
	v_bitop3_b32 v26, v3, s6, v0 bitop3:0x6c
	s_movk_i32 s6, 0xb0
; #define GAS __attribute__((address_space(1)))
; #define LAS __attribute__((address_space(3)))
; __device__ __forceinline__ void attn_unit(const bool FINAL, const bool HN, LAS unsigned char* wl, const bf16_t* qb, const bf16_t* kb, const bf16_t* vb, int tq0, int dil, float sl, bf16x8 (&qr)[8], const bf16_t* nqb, const bf16_t* nkb, const bf16_t* nvb, int ntq0, int ndil, ...
;     const int r32 = lane & 31, hi = lane >> 5;
;     LAS unsigned char* kbuf = wl; LAS unsigned char* vbuf = wl + 8192;
;     const int jlo = 64 - tq0 / dil, jhi = 64 + (SEQ - 1 - tq0) / dil;
;     const float lo_i = (float)max(-64, jlo - 64 - r32), hi_i = (float)min(64, jhi - 64 - r32);
;     const bool interior = (jlo <= 0) && (jhi >= 159);
;     float m_run = -1e30f, l_run = 0.f;
;     f32x16 oT[4];
; #pragma unroll
;     for (int d0 = 0; d0 < 4; ++d0)
; #pragma unroll
;         for (int r = 0; r < 16; ++r) oT[d0][r] = 0.f;
;     asm volatile("s_waitcnt vmcnt(0)" ::: "memory");
; #pragma unroll
;     for (int s = 0; s < 8; ++s) asm volatile("" : "+v"(qr[s]));
;     long q8[8];
; #pragma unroll
;     for (int s = 0; s < 8; ++s) q8[s] = bf16x8_to_fp8(qr[s]);
;     f32x2 st1 = {0.f, 0.f}, st2 = {0.f, 0.f};
;     if (FINAL) { const size_t tqs = (size_t)(tq0 + dil * r32) * 2; st1 = *(const GAS f32x2*)(ml0 + tqs); st2 = *(const GAS f32x2*)(ml1 + tqs); }
;     const int rr0 = lane >> 4, cs = lane & 15;
;     const LAS unsigned char* krd = kbuf + r32 * 128 + hi * 8;
;     const int kx = (r32 & 7) << 4;
;     ...
;         {
;             int vl_ = lane; asm volatile("" : "+v"(vl_));
;             const int vg = vl_ & 15, vgrp = vl_ >> 4, vr = TRB8_MAP ? (vg & 7) : (vg >> 1), vc = TRB8_MAP ? (vg >> 3) : (vg & 1);
;             const unsigned vb0 = (unsigned)(uintptr_t)vbuf + (unsigned)((8 * (vgrp >> 1) + vr) * 128 + 8 * vc);
;             long vf[4][2];
	v_bitop3_b32 v27, v3, s6, v0 bitop3:0x6c
	s_movk_i32 s6, 0xc0
	v_ashrrev_i32_e32 v174, 4, v131
	v_lshlrev_b32_e32 v1, 7, v173
	v_mov_b32_e32 v4, 0x70
	s_movk_i32 s7, 0x50
	s_movk_i32 s8, 0x60
	v_bitop3_b32 v28, v3, s6, v0 bitop3:0x6c
	s_movk_i32 s6, 0xd0
	v_add3_u32 v1, s83, v1, v2
	v_bitop3_b32 v7, v3, 16, v4 bitop3:0x6c
	v_bitop3_b32 v9, v3, 32, v4 bitop3:0x6c
	v_bitop3_b32 v11, v3, 48, v4 bitop3:0x6c
	v_bitop3_b32 v13, v3, 64, v4 bitop3:0x6c
	v_bitop3_b32 v14, v3, s7, v4 bitop3:0x6c
	v_bitop3_b32 v15, v3, s8, v4 bitop3:0x6c
	v_bitop3_b32 v29, v3, s6, v0 bitop3:0x6c
	s_movk_i32 s6, 0xe0
	v_add_u32_e32 v2, 4, v174
	v_add_u32_e32 v4, 8, v174
	v_add_u32_e32 v6, 12, v174
	v_add_u32_e32 v8, 20, v174
	v_add_u32_e32 v10, 24, v174
	v_add_u32_e32 v12, 28, v174
	v_bitop3_b32 v17, v3, 16, v0 bitop3:0x6c
	v_bitop3_b32 v18, v3, 32, v0 bitop3:0x6c
	v_bitop3_b32 v19, v3, 48, v0 bitop3:0x6c
	v_bitop3_b32 v20, v3, 64, v0 bitop3:0x6c
	v_bitop3_b32 v21, v3, s7, v0 bitop3:0x6c
	v_bitop3_b32 v22, v3, s8, v0 bitop3:0x6c
	v_bitop3_b32 v30, v3, s6, v0 bitop3:0x6c
	v_xor_b32_e32 v0, v174, v131
	v_xor_b32_e32 v2, v2, v131
	v_xor_b32_e32 v4, v4, v131
	v_xor_b32_e32 v6, v6, v131
	v_xor_b32_e32 v8, v8, v131
	v_xor_b32_e32 v10, v10, v131
	v_xor_b32_e32 v12, v12, v131
	v_readlane_b32 s21, v254, 3
	s_movk_i32 s9, 0xf0
	v_lshlrev_b32_e32 v0, 3, v0
	v_lshlrev_b32_e32 v2, 3, v2
	v_lshlrev_b32_e32 v4, 3, v4
	v_lshlrev_b32_e32 v6, 3, v6
	v_lshlrev_b32_e32 v8, 3, v8
	v_lshlrev_b32_e32 v10, 3, v10
	v_lshlrev_b32_e32 v12, 3, v12
	v_and_b32_e32 v5, 0x70, v3
	v_and_b32_e32 v177, 0xf0, v3
	v_bitop3_b32 v3, v3, s9, v3 bitop3:0xc
	v_lshl_add_u32 v31, v174, 8, s83
	v_and_b32_e32 v0, 0x78, v0
	v_and_b32_e32 v2, 0x78, v2
	v_and_b32_e32 v4, 0x78, v4
	v_and_b32_e32 v6, 0x78, v6
	v_and_b32_e32 v8, 0x78, v8
	v_and_b32_e32 v10, 0x78, v10
	v_and_b32_e32 v12, 0x78, v12
	s_mov_b32 s18, 0x41200000
	s_mov_b32 s20, 0x41800000
	s_mov_b32 s22, 0x41900000
	s_mov_b32 s24, 0x41c00000
	s_mov_b32 s26, 0x41d00000
	s_mov_b32 s28, 0x42000000
	s_mov_b32 s30, 0x42080000
	s_mov_b32 s66, 0x42800000
	s_mov_b32 s67, 0
	v_cmp_gt_u32_e64 s[4:5], 32, v131
	s_and_b32 s87, s86, 3
	v_add_u32_e32 v178, v1, v5
	v_add_u32_e32 v179, v1, v7
	v_add_u32_e32 v180, v1, v9
	v_add_u32_e32 v181, v1, v11
	v_add_u32_e32 v182, v1, v13
	v_add_u32_e32 v183, v1, v14
	v_add_u32_e32 v184, v1, v15
	v_add_u32_e32 v185, v1, v16
	s_mov_b32 s89, 0xf149f2ca
	s_mov_b32 s19, 0x41300000
	s_mov_b32 s21, 0x41880000
	s_mov_b32 s23, 0x41980000
	s_mov_b32 s25, 0x41c80000
	s_mov_b32 s27, 0x41d80000
	s_mov_b32 s29, 0x42040000
	s_mov_b32 s31, 0x420c0000
	s_mov_b32 s90, 0xc2800000
	v_add_u32_e32 v186, v176, v17
	v_add_u32_e32 v187, v176, v18
	v_add_u32_e32 v188, v176, v19
	v_add_u32_e32 v189, v176, v20
	v_add_u32_e32 v190, v176, v21
	v_add_u32_e32 v191, v176, v22
	v_add_u32_e32 v192, v176, v23
	v_add_u32_e32 v193, v176, v24
	v_add_u32_e32 v194, v176, v25
	v_add_u32_e32 v195, v176, v26
	v_add_u32_e32 v196, v176, v27
	v_add_u32_e32 v197, v176, v28
	v_add_u32_e32 v198, v176, v29
	v_add_u32_e32 v199, v176, v30
	v_add_u32_e32 v200, v176, v3
	v_add_u32_e32 v201, v31, v177
	v_lshlrev_b32_e32 v112, 1, v0
	v_lshlrev_b32_e32 v116, 1, v2
	v_lshlrev_b32_e32 v118, 1, v4
	v_lshlrev_b32_e32 v120, 1, v6
	v_lshlrev_b32_e32 v122, 1, v8
	v_lshlrev_b32_e32 v124, 1, v10
	v_lshlrev_b32_e32 v126, 1, v12
	v_mov_b32_e32 v202, 0xf149f2ca
	v_mov_b32_e32 v203, v113
	s_mov_b32 s91, s86
	s_mov_b64 s[34:35], s[54:55]
	s_mov_b64 s[36:37], s[56:57]
	s_mov_b64 s[42:43], s[16:17]
	s_mov_b64 s[40:41], s[44:45]
	v_bfe_u32 v212, v131, 1, 3
	v_lshrrev_b32_e32 v213, 2, v131
	v_lshlrev_b32_e32 v214, 3, v131
	v_lshrrev_b32_e32 v215, 4, v131
	v_and_b32_e32 v213, 0x1fffff8, v213
	v_or_b32_e32 v213, v213, v212
	v_and_b32_e32 v214, 8, v214
	v_lshl_add_u32 v216, v213, 7, v214
	v_bitop3_b32 v215, v215, v212, 1 bitop3:0x6c
	v_bfe_u32 v213, v131, 4, 1
	v_lshl_add_u32 v208, v215, 4, v216
	v_bitop3_b32 v215, v213, v212, 2 bitop3:0x36
	v_lshl_add_u32 v209, v215, 4, v216
	v_bitop3_b32 v215, v213, v212, 4 bitop3:0x36
	v_lshl_add_u32 v210, v215, 4, v216
	v_bitop3_b32 v215, v213, v212, 6 bitop3:0x36
	v_lshl_add_u32 v211, v215, 4, v216
	s_branch .LBB0_366

; #define GAS __attribute__((address_space(1)))
; #define LAS __attribute__((address_space(3)))
; #define SBAR() __builtin_amdgcn_sched_barrier(0)
; __device__ __forceinline__ void attn_unit(const bool FINAL, const bool HN, LAS unsigned char* wl, const bf16_t* qb, const bf16_t* kb, const bf16_t* vb, int tq0, int dil, float sl, bf16x8 (&qr)[8], const bf16_t* nqb, const bf16_t* nkb, const bf16_t* nvb, int ntq0, int ndil, ...
;     ...
;     for (int n = 0; n < 5; ++n) {
;         if (n > 0) asm volatile("s_waitcnt vmcnt(4)" ::: "memory");
;         SBAR();
;         long kf[8];
; #pragma unroll
;         for (int s = 0; s < 8; ++s) kf[s] = *(const LAS long*)(krd + ((16 * s) ^ kx));
;         asm volatile("s_waitcnt lgkmcnt(0)" ::: "memory"); SBAR();
;         unsigned toff[4];
;         if (n < 4 || HN) {
;             const bf16_t* kbp = (n < 4) ? kb : nkb; const int ktq = (n < 4) ? tq0 : ntq0, kdl = (n < 4) ? dil : ndil, ktl = (n < 4) ? n + 1 : 0;
;             int kl = lane; asm volatile("" : "+v"(kl));
;             const int kr0 = kl >> 3; const unsigned kc0 = (unsigned)(((kl & 7) ^ kr0) << 4);
;             const int kt0 = ktq + kdl * (32 * ktl + kr0 - 64), kd8 = 8 * kdl;
;             if (interior && n < 4) {
; #pragma unroll
;                 for (int i = 0; i < 4; ++i) toff[i] = ((unsigned)(kt0 + i * kd8) << 7) + kc0;
;             } else {
; #pragma unroll
;                 for (int i = 0; i < 4; ++i) { int tkn = kt0 + i * kd8; tkn = tkn < 0 ? 0 : (tkn > SEQ - 1 ? SEQ - 1 : tkn); toff[i] = ((unsigned)tkn << 7) + kc0; }
;             }
; #pragma unroll
;             for (int i = 0; i < 4; ++i) __builtin_amdgcn_global_load_lds((const unsigned*)((const GAS char*)kbp + toff[i]), (LAS unsigned*)(kbuf + i * 1024), 16, 0, 0);
;         }
.LBB0_375:
	ds_read_b64 v[64:65], v178
	ds_read_b64 v[164:165], v179
	ds_read_b64 v[162:163], v180
	ds_read_b64 v[160:161], v181
	ds_read_b64 v[158:159], v182
	ds_read_b64 v[152:153], v183
	ds_read_b64 v[154:155], v184
	ds_read_b64 v[156:157], v185
	s_waitcnt lgkmcnt(0)
	s_cmpk_lg_i32 s15, 0x80
	s_cselect_b64 s[70:71], -1, 0
	s_nor_b64 s[72:73], s[46:47], s[70:71]
	s_movk_i32 s6, 0x80
	s_and_b64 vcc, exec, s[72:73]
	s_cbranch_vccnz .LBB0_381
	s_and_b64 s[6:7], s[58:59], s[70:71]
	s_and_b64 s[6:7], s[6:7], s[74:75]
	s_and_b64 vcc, exec, s[6:7]
	s_cbranch_vccz mk_p2a_dma_slow
	s_lshl_b32 s8, s88, 12
	s_mov_b32 m0, s83
	v_add_u32_e32 v204, s8, v204
	v_add_u32_e32 v127, s8, v127
	v_add_u32_e32 v125, s8, v125
	v_add_u32_e32 v123, s8, v123
	global_load_lds_dwordx4 v204, s[54:55]
	s_mov_b32 m0, s76
	s_nop 0
	global_load_lds_dwordx4 v127, s[54:55]
	s_mov_b32 m0, s77
	s_nop 0
	global_load_lds_dwordx4 v125, s[54:55]
	s_mov_b32 m0, s78
	s_nop 0
	global_load_lds_dwordx4 v123, s[54:55]
	s_mov_b32 s6, s15
	s_branch .LBB0_381
mk_p2a_dma_slow:
	s_and_b64 s[6:7], s[70:71], exec
	s_cselect_b32 s8, s92, s67
	s_cselect_b32 s9, s88, s39
	s_sub_i32 s10, s15, 32
	v_mov_b32_e32 v66, v131
	s_and_b64 s[6:7], s[70:71], exec
	s_cselect_b32 s6, s10, 0xffffffc0
	v_ashrrev_i32_e32 v67, 3, v66
	v_add_u32_e32 v68, s6, v67
	v_mul_lo_u32 v68, v68, s9
	v_add_u32_e32 v71, s8, v68
	s_lshl_b32 s8, s9, 3
	s_and_b64 s[10:11], s[58:59], s[70:71]
	s_mov_b64 s[6:7], -1
	s_and_b64 vcc, exec, s[10:11]
	v_add_u32_e32 v73, s8, v71
	s_cbranch_vccnz .LBB0_378
	v_add_u32_e32 v68, s8, v71
	v_add_u32_e32 v72, s8, v68
	v_med3_i32 v70, v71, 0, v172
	v_med3_i32 v69, v68, 0, v172
	v_med3_i32 v68, v72, 0, v172
	v_add_u32_e32 v72, s8, v72
	v_lshlrev_b32_e32 v68, 7, v68
	v_med3_i32 v72, v72, 0, v172
	v_lshlrev_b32_e32 v70, 7, v70
	s_mov_b64 s[6:7], 0

; __device__ __forceinline__ void attn_unit(const bool FINAL, const bool HN, LAS unsigned char* wl, const bf16_t* qb, const bf16_t* kb, const bf16_t* vb, int tq0, int dil, float sl, bf16x8 (&qr)[8], const bf16_t* nqb, const bf16_t* nkb, const bf16_t* nvb, int ntq0, int ndil, ...
;     ...
;         { auto rr = __builtin_amdgcn_permlane32_swap(__float_as_uint(tmax), __float_as_uint(tmax), false, false); tmax = fmaxf(__uint_as_float(rr[0]), __uint_as_float(rr[1])); }
;         float mn = m_run, alpha = 1.f;
;         if (!__all(tmax - m_run <= AT_THR)) { mn = fmaxf(m_run, tmax); alpha = __builtin_amdgcn_exp2f(m_run - mn); m_run = mn;
;             if (n > 0) {
; #pragma unroll
;             for (int d0 = 0; d0 < 4; ++d0)
; #pragma unroll
;                 for (int r = 0; r < 16; ++r) oT[d0][r] *= alpha; } }
.LBB0_394:
	s_nop 8
	v_mov_b32_e32 v64, v159
	s_nop 1
	v_permlane32_swap_b32_e32 v159, v64
	v_max_f32_e32 v64, v159, v64
	v_sub_f32_e32 v65, v64, v205
	s_mov_b32 s6, 0x41000000
	v_cmp_ge_f32_e32 vcc, s6, v65
	s_cmp_eq_u64 vcc, exec
	v_mov_b32_e32 v66, 1.0
	s_cbranch_scc1 .LBB0_397
	v_max_f32_e32 v64, v64, v64
	v_max_f32_e32 v65, v205, v205
	v_max_f32_e32 v64, v65, v64
	v_sub_f32_e32 v65, v205, v64
	v_exp_f32_e32 v66, v65
	s_andn2_b64 vcc, exec, s[74:75]
	s_cbranch_vccnz .LBB0_398
	v_pk_mul_f32 v[62:63], v[62:63], v[66:67] op_sel_hi:[1,0]
	v_pk_mul_f32 v[60:61], v[60:61], v[66:67] op_sel_hi:[1,0]
	v_pk_mul_f32 v[58:59], v[58:59], v[66:67] op_sel_hi:[1,0]
	v_pk_mul_f32 v[56:57], v[56:57], v[66:67] op_sel_hi:[1,0]
	v_pk_mul_f32 v[54:55], v[54:55], v[66:67] op_sel_hi:[1,0]
	v_pk_mul_f32 v[52:53], v[52:53], v[66:67] op_sel_hi:[1,0]
	v_pk_mul_f32 v[50:51], v[50:51], v[66:67] op_sel_hi:[1,0]
	v_pk_mul_f32 v[48:49], v[48:49], v[66:67] op_sel_hi:[1,0]
	v_pk_mul_f32 v[46:47], v[46:47], v[66:67] op_sel_hi:[1,0]
	v_pk_mul_f32 v[44:45], v[44:45], v[66:67] op_sel_hi:[1,0]
	v_pk_mul_f32 v[42:43], v[42:43], v[66:67] op_sel_hi:[1,0]
	v_pk_mul_f32 v[40:41], v[40:41], v[66:67] op_sel_hi:[1,0]
	v_pk_mul_f32 v[38:39], v[38:39], v[66:67] op_sel_hi:[1,0]
	v_pk_mul_f32 v[36:37], v[36:37], v[66:67] op_sel_hi:[1,0]
	v_pk_mul_f32 v[34:35], v[34:35], v[66:67] op_sel_hi:[1,0]
	v_pk_mul_f32 v[32:33], v[32:33], v[66:67] op_sel_hi:[1,0]
	v_pk_mul_f32 v[30:31], v[30:31], v[66:67] op_sel_hi:[1,0]
	v_pk_mul_f32 v[28:29], v[28:29], v[66:67] op_sel_hi:[1,0]
	v_pk_mul_f32 v[26:27], v[26:27], v[66:67] op_sel_hi:[1,0]
	v_pk_mul_f32 v[24:25], v[24:25], v[66:67] op_sel_hi:[1,0]
	v_pk_mul_f32 v[22:23], v[22:23], v[66:67] op_sel_hi:[1,0]
	v_pk_mul_f32 v[20:21], v[20:21], v[66:67] op_sel_hi:[1,0]
	v_pk_mul_f32 v[18:19], v[18:19], v[66:67] op_sel_hi:[1,0]
	v_pk_mul_f32 v[16:17], v[16:17], v[66:67] op_sel_hi:[1,0]
	v_pk_mul_f32 v[14:15], v[14:15], v[66:67] op_sel_hi:[1,0]
	v_pk_mul_f32 v[12:13], v[12:13], v[66:67] op_sel_hi:[1,0]
	v_pk_mul_f32 v[10:11], v[10:11], v[66:67] op_sel_hi:[1,0]
	v_pk_mul_f32 v[8:9], v[8:9], v[66:67] op_sel_hi:[1,0]
	v_pk_mul_f32 v[6:7], v[6:7], v[66:67] op_sel_hi:[1,0]
	v_pk_mul_f32 v[4:5], v[4:5], v[66:67] op_sel_hi:[1,0]
	v_pk_mul_f32 v[2:3], v[2:3], v[66:67] op_sel_hi:[1,0]
	v_pk_mul_f32 v[0:1], v[0:1], v[66:67] op_sel_hi:[1,0]
	s_branch .LBB0_398

; #define AT_PK8(P, BASE, OUT) do { const unsigned a4 = pg8::pk_fp8x4((f32x4){P[BASE + 0], P[BASE + 1], P[BASE + 2], P[BASE + 3]}), b4 = pg8::pk_fp8x4((f32x4){P[BASE + 4], P[BASE + 5], P[BASE + 6], P[BASE + 7]}); \
;         auto r0 = __builtin_amdgcn_permlane32_swap(a4, b4, false, false); OUT = (long)(((unsigned long long)r0[1] << 32) | (unsigned long long)r0[0]); } while (0)
; __device__ __forceinline__ void attn_unit(const bool FINAL, const bool HN, LAS unsigned char* wl, const bf16_t* qb, const bf16_t* kb, const bf16_t* vb, int tq0, int dil, float sl, bf16x8 (&qr)[8], const bf16_t* nqb, const bf16_t* nkb, const bf16_t* nvb, int ntq0, int ndil, ...
;     ...
;         float ps = 0.f;
; #pragma unroll
;         for (int r = 0; r < 16; ++r) { p[r] = __builtin_amdgcn_exp2f(p[r] - mn); ps += p[r]; }
;         { auto rr = __builtin_amdgcn_permlane32_swap(__float_as_uint(ps), __float_as_uint(ps), false, false); ps = __uint_as_float(rr[0]) + __uint_as_float(rr[1]); }
;         l_run = l_run * alpha + ps;
;         long pa0, pa1;
;     ...
;         AT_PK8(p, 0, pa0); AT_PK8(p, 8, pa1);
;     ...
;         if (n < 4 || HN) asm volatile("s_waitcnt vmcnt(4)" ::: "memory");
;         else asm volatile("s_waitcnt vmcnt(0)" ::: "memory");
.LBB0_398:
	v_pk_add_f32 v[152:153], v[152:153], v[64:65] op_sel_hi:[1,0] neg_lo:[0,1] neg_hi:[0,1]
	v_pk_add_f32 v[154:155], v[154:155], v[64:65] op_sel_hi:[1,0] neg_lo:[0,1] neg_hi:[0,1]
	v_pk_add_f32 v[156:157], v[156:157], v[64:65] op_sel_hi:[1,0] neg_lo:[0,1] neg_hi:[0,1]
	v_pk_add_f32 v[160:161], v[160:161], v[64:65] op_sel_hi:[1,0] neg_lo:[0,1] neg_hi:[0,1]
	v_pk_add_f32 v[162:163], v[162:163], v[64:65] op_sel_hi:[1,0] neg_lo:[0,1] neg_hi:[0,1]
	v_pk_add_f32 v[166:167], v[166:167], v[64:65] op_sel_hi:[1,0] neg_lo:[0,1] neg_hi:[0,1]
	v_pk_add_f32 v[168:169], v[168:169], v[64:65] op_sel_hi:[1,0] neg_lo:[0,1] neg_hi:[0,1]
	v_pk_add_f32 v[170:171], v[170:171], v[64:65] op_sel_hi:[1,0] neg_lo:[0,1] neg_hi:[0,1]
	v_exp_f32_e32 v152, v152
	v_exp_f32_e32 v153, v153
	v_exp_f32_e32 v154, v154
	v_exp_f32_e32 v155, v155
	v_exp_f32_e32 v156, v156
	v_exp_f32_e32 v157, v157
	v_exp_f32_e32 v160, v160
	v_exp_f32_e32 v161, v161
	v_exp_f32_e32 v162, v162
	v_exp_f32_e32 v163, v163
	v_exp_f32_e32 v166, v166
	v_exp_f32_e32 v167, v167
	v_exp_f32_e32 v168, v168
	v_exp_f32_e32 v169, v169
	v_exp_f32_e32 v170, v170
	v_exp_f32_e32 v171, v171
	v_cvt_pk_fp8_f32 v68, v152, v153
	v_cvt_pk_fp8_f32 v69, v156, v157
	v_cvt_pk_fp8_f32 v70, v162, v163
	v_cvt_pk_fp8_f32 v71, v168, v169
	v_cvt_pk_fp8_f32 v68, v154, v155 op_sel:[0,0,1]
	v_cvt_pk_fp8_f32 v69, v160, v161 op_sel:[0,0,1]
	v_cvt_pk_fp8_f32 v70, v166, v167 op_sel:[0,0,1]
	v_cvt_pk_fp8_f32 v71, v170, v171 op_sel:[0,0,1]
	v_pk_add_f32 v[72:73], v[152:153], v[154:155]
	v_pk_add_f32 v[74:75], v[156:157], v[160:161]
	v_pk_add_f32 v[76:77], v[162:163], v[166:167]
	v_pk_add_f32 v[78:79], v[168:169], v[170:171]
	v_pk_add_f32 v[72:73], v[72:73], v[74:75]
	v_pk_add_f32 v[76:77], v[76:77], v[78:79]
	v_pk_add_f32 v[72:73], v[72:73], v[76:77]
	v_add_f32_e32 v65, v72, v73
	v_mov_b32_e32 v67, v65
	s_nop 1
	v_permlane32_swap_b32_e32 v65, v67
	v_permlane32_swap_b32_e32 v68, v69
	v_permlane32_swap_b32_e32 v70, v71
	s_mov_b64 s[6:7], -1
	s_and_b64 vcc, exec, s[72:73]
	s_cbranch_vccz .LBB0_400
	s_waitcnt vmcnt(0)
	s_mov_b64 s[6:7], 0

; #define GAS __attribute__((address_space(1)))
; #define LAS __attribute__((address_space(3)))
; #define SBAR() __builtin_amdgcn_sched_barrier(0)
; #define AT_RD8(D0) do { const unsigned va_ = vb0 + (unsigned)((((2 * D0 + (vgrp & 1)) ^ vr) & 7) << 4); vf[D0][0] = tr8_read<0>(va_); vf[D0][1] = tr8_read<2048>(va_); } while (0)
; __device__ __forceinline__ void attn_unit(const bool FINAL, const bool HN, LAS unsigned char* wl, const bf16_t* qb, const bf16_t* kb, const bf16_t* vb, int tq0, int dil, float sl, bf16x8 (&qr)[8], const bf16_t* nqb, const bf16_t* nkb, const bf16_t* nvb, int ntq0, int ndil, ...
;     ...
;         {
;             int vl_ = lane; asm volatile("" : "+v"(vl_));
;             const int vg = vl_ & 15, vgrp = vl_ >> 4, vr = TRB8_MAP ? (vg & 7) : (vg >> 1), vc = TRB8_MAP ? (vg >> 3) : (vg & 1);
;             const unsigned vb0 = (unsigned)(uintptr_t)vbuf + (unsigned)((8 * (vgrp >> 1) + vr) * 128 + 8 * vc);
;             long vf[4][2];
;     ...
;             AT_RD8(0); AT_RD8(1); AT_RD8(2); AT_RD8(3);
;     ...
;             asm volatile("s_waitcnt lgkmcnt(0)" ::: "memory"); SBAR();
;             if (n < 4) {
; #pragma unroll
;                 for (int i = 0; i < 4; ++i) __builtin_amdgcn_global_load_lds((const unsigned*)((const GAS char*)vb + toff[i]), (LAS unsigned*)(vbuf + i * 1024), 16, 0, 0); }
; #pragma unroll
;             for (int d0 = 0; d0 < 4; ++d0) {
;                 oT[d0] = __builtin_amdgcn_mfma_f32_32x32x16_fp8_fp8(vf[d0][0], pa0, oT[d0], 0, 0, 0);
;                 oT[d0] = __builtin_amdgcn_mfma_f32_32x32x16_fp8_fp8(vf[d0][1], pa1, oT[d0], 0, 0, 0); }
;         }
.LBB0_402:
	v_add_u32_e32 v160, s79, v208
	v_add_u32_e32 v161, s79, v209
	v_add_u32_e32 v162, s79, v210
	v_add_u32_e32 v163, s79, v211
	ds_read_b64_tr_b8 v[76:77], v160 offset:0
	ds_read_b64_tr_b8 v[74:75], v160 offset:0x800
	ds_read_b64_tr_b8 v[152:153], v161 offset:0
	ds_read_b64_tr_b8 v[78:79], v161 offset:0x800
	ds_read_b64_tr_b8 v[156:157], v162 offset:0
	ds_read_b64_tr_b8 v[154:155], v162 offset:0x800
	ds_read_b64_tr_b8 v[158:159], v163 offset:0
	ds_read_b64_tr_b8 v[72:73], v163 offset:0x800
	s_waitcnt lgkmcnt(0)
	s_andn2_b64 vcc, exec, s[70:71]
	s_cbranch_vccnz .LBB0_404
	s_mov_b32 m0, s79
	s_nop 0
	global_load_lds_dwordx4 v204, s[56:57]
	s_mov_b32 m0, s80
	s_nop 0
	global_load_lds_dwordx4 v127, s[56:57]
	s_mov_b32 m0, s81
	s_nop 0
	global_load_lds_dwordx4 v125, s[56:57]
	s_mov_b32 m0, s82
	s_nop 0
	global_load_lds_dwordx4 v123, s[56:57]

; #define AT_PK8(P, BASE, OUT) do { const unsigned a4 = pg8::pk_fp8x4((f32x4){P[BASE + 0], P[BASE + 1], P[BASE + 2], P[BASE + 3]}), b4 = pg8::pk_fp8x4((f32x4){P[BASE + 4], P[BASE + 5], P[BASE + 6], P[BASE + 7]}); \
;         auto r0 = __builtin_amdgcn_permlane32_swap(a4, b4, false, false); OUT = (long)(((unsigned long long)r0[1] << 32) | (unsigned long long)r0[0]); } while (0)
; __device__ __forceinline__ void attn_unit(const bool FINAL, const bool HN, LAS unsigned char* wl, const bf16_t* qb, const bf16_t* kb, const bf16_t* vb, int tq0, int dil, float sl, bf16x8 (&qr)[8], const bf16_t* nqb, const bf16_t* nkb, const bf16_t* nvb, int ntq0, int ndil, ...
;     ...
;         float ps = 0.f;
; #pragma unroll
;         for (int r = 0; r < 16; ++r) { p[r] = __builtin_amdgcn_exp2f(p[r] - mn); ps += p[r]; }
;         { auto rr = __builtin_amdgcn_permlane32_swap(__float_as_uint(ps), __float_as_uint(ps), false, false); ps = __uint_as_float(rr[0]) + __uint_as_float(rr[1]); }
;         l_run = l_run * alpha + ps;
;         long pa0, pa1;
;     ...
;         AT_PK8(p, 0, pa0); AT_PK8(p, 8, pa1);
;     ...
;         if (n < 4 || HN) asm volatile("s_waitcnt vmcnt(4)" ::: "memory");
;         else asm volatile("s_waitcnt vmcnt(0)" ::: "memory");
.LBB0_501:
	v_pk_add_f32 v[138:139], v[138:139], v[160:161] op_sel:[0,1] op_sel_hi:[1,1] neg_lo:[0,1] neg_hi:[0,1]
	v_pk_add_f32 v[140:141], v[140:141], v[160:161] op_sel:[0,1] op_sel_hi:[1,1] neg_lo:[0,1] neg_hi:[0,1]
	v_pk_add_f32 v[142:143], v[142:143], v[160:161] op_sel:[0,1] op_sel_hi:[1,1] neg_lo:[0,1] neg_hi:[0,1]
	v_pk_add_f32 v[144:145], v[144:145], v[160:161] op_sel:[0,1] op_sel_hi:[1,1] neg_lo:[0,1] neg_hi:[0,1]
	v_pk_add_f32 v[146:147], v[146:147], v[160:161] op_sel:[0,1] op_sel_hi:[1,1] neg_lo:[0,1] neg_hi:[0,1]
	v_pk_add_f32 v[150:151], v[150:151], v[160:161] op_sel:[0,1] op_sel_hi:[1,1] neg_lo:[0,1] neg_hi:[0,1]
	v_pk_add_f32 v[152:153], v[152:153], v[160:161] op_sel:[0,1] op_sel_hi:[1,1] neg_lo:[0,1] neg_hi:[0,1]
	v_pk_add_f32 v[154:155], v[154:155], v[160:161] op_sel:[0,1] op_sel_hi:[1,1] neg_lo:[0,1] neg_hi:[0,1]
	v_exp_f32_e32 v138, v138
	v_exp_f32_e32 v139, v139
	v_exp_f32_e32 v140, v140
	v_exp_f32_e32 v141, v141
	v_exp_f32_e32 v142, v142
	v_exp_f32_e32 v143, v143
	v_exp_f32_e32 v144, v144
	v_exp_f32_e32 v145, v145
	v_exp_f32_e32 v146, v146
	v_exp_f32_e32 v147, v147
	v_exp_f32_e32 v150, v150
	v_exp_f32_e32 v151, v151
	v_exp_f32_e32 v152, v152
	v_exp_f32_e32 v153, v153
	v_exp_f32_e32 v154, v154
	v_exp_f32_e32 v155, v155
	v_cvt_pk_fp8_f32 v66, v138, v139
	v_cvt_pk_fp8_f32 v67, v142, v143
	v_cvt_pk_fp8_f32 v68, v146, v147
	v_cvt_pk_fp8_f32 v69, v152, v153
	v_cvt_pk_fp8_f32 v66, v140, v141 op_sel:[0,0,1]
	v_cvt_pk_fp8_f32 v67, v144, v145 op_sel:[0,0,1]
	v_cvt_pk_fp8_f32 v68, v150, v151 op_sel:[0,0,1]
	v_cvt_pk_fp8_f32 v69, v154, v155 op_sel:[0,0,1]
	v_pk_add_f32 v[70:71], v[138:139], v[140:141]
	v_pk_add_f32 v[72:73], v[142:143], v[144:145]
	v_pk_add_f32 v[74:75], v[146:147], v[150:151]
	v_pk_add_f32 v[76:77], v[152:153], v[154:155]
	v_pk_add_f32 v[70:71], v[70:71], v[72:73]
	v_pk_add_f32 v[74:75], v[74:75], v[76:77]
	v_pk_add_f32 v[70:71], v[70:71], v[74:75]
	v_add_f32_e32 v142, v70, v71
	v_mov_b32_e32 v143, v142
	s_nop 1
	v_permlane32_swap_b32_e32 v142, v143
	v_permlane32_swap_b32_e32 v66, v67
	v_permlane32_swap_b32_e32 v68, v69
	s_mov_b64 s[4:5], -1
	s_and_b64 vcc, exec, s[78:79]
	s_cbranch_vccz .LBB0_503
	s_waitcnt vmcnt(0)
	s_mov_b64 s[4:5], 0
